# chunk prep: QD/KDT record emission (waves 4-7) rewritten as straight-line code with all LDS reads batched under counted lgkmcnt; next-chunk raw-row prefetch address arithmetic hoisted out of the chunk
# speedup vs baseline: 1.0077x; 1.0077x over previous
.LBB0_110:
	s_mov_b32 s6, 0x7a44c6b
	v_mov_b32_e32 v146, v242
	v_min_u32_e32 v146, 0xc8f, v146
	v_mul_hi_u32 v147, v146, s6
	v_lshrrev_b32_e32 v147, 5, v147
	v_mul_u32_u24_e32 v148, 0x430, v147
	v_sub_u32_e32 v148, v146, v148
	v_lshrrev_b32_e32 v149, 4, v148
	v_and_b32_e32 v148, 15, v148
	v_lshlrev_b32_e32 v148, 4, v148
	v_lshl_add_u32 v148, v147, 10, v148
	v_max_u32_e32 v147, 3, v149
	v_mad_u32_u24 v132, v149, s87, v148
	v_mad_u32_u24 v139, v147, s87, v148
	v_add_u32_e32 v146, 0x200, v242
	v_min_u32_e32 v146, 0xc8f, v146
	v_mul_hi_u32 v147, v146, s6
	v_lshrrev_b32_e32 v147, 5, v147
	v_mul_u32_u24_e32 v148, 0x430, v147
	v_sub_u32_e32 v148, v146, v148
	v_lshrrev_b32_e32 v149, 4, v148
	v_and_b32_e32 v148, 15, v148
	v_lshlrev_b32_e32 v148, 4, v148
	v_lshl_add_u32 v148, v147, 10, v148
	v_max_u32_e32 v147, 3, v149
	v_mad_u32_u24 v133, v149, s87, v148
	v_mad_u32_u24 v140, v147, s87, v148
	v_add_u32_e32 v146, 0x400, v242
	v_min_u32_e32 v146, 0xc8f, v146
	v_mul_hi_u32 v147, v146, s6
	v_lshrrev_b32_e32 v147, 5, v147
	v_mul_u32_u24_e32 v148, 0x430, v147
	v_sub_u32_e32 v148, v146, v148
	v_lshrrev_b32_e32 v149, 4, v148
	v_and_b32_e32 v148, 15, v148
	v_lshlrev_b32_e32 v148, 4, v148
	v_lshl_add_u32 v148, v147, 10, v148
	v_max_u32_e32 v147, 3, v149
	v_mad_u32_u24 v134, v149, s87, v148
	v_mad_u32_u24 v141, v147, s87, v148
	v_add_u32_e32 v146, 0x600, v242
	v_min_u32_e32 v146, 0xc8f, v146
	v_mul_hi_u32 v147, v146, s6
	v_lshrrev_b32_e32 v147, 5, v147
	v_mul_u32_u24_e32 v148, 0x430, v147
	v_sub_u32_e32 v148, v146, v148
	v_lshrrev_b32_e32 v149, 4, v148
	v_and_b32_e32 v148, 15, v148
	v_lshlrev_b32_e32 v148, 4, v148
	v_lshl_add_u32 v148, v147, 10, v148
	v_max_u32_e32 v147, 3, v149
	v_mad_u32_u24 v135, v149, s87, v148
	v_mad_u32_u24 v142, v147, s87, v148
	v_add_u32_e32 v146, 0x800, v242
	v_min_u32_e32 v146, 0xc8f, v146
	v_mul_hi_u32 v147, v146, s6
	v_lshrrev_b32_e32 v147, 5, v147
	v_mul_u32_u24_e32 v148, 0x430, v147
	v_sub_u32_e32 v148, v146, v148
	v_lshrrev_b32_e32 v149, 4, v148
	v_and_b32_e32 v148, 15, v148
	v_lshlrev_b32_e32 v148, 4, v148
	v_lshl_add_u32 v148, v147, 10, v148
	v_max_u32_e32 v147, 3, v149
	v_mad_u32_u24 v136, v149, s87, v148
	v_mad_u32_u24 v143, v147, s87, v148
	v_add_u32_e32 v146, 0xa00, v242
	v_min_u32_e32 v146, 0xc8f, v146
	v_mul_hi_u32 v147, v146, s6
	v_lshrrev_b32_e32 v147, 5, v147
	v_mul_u32_u24_e32 v148, 0x430, v147
	v_sub_u32_e32 v148, v146, v148
	v_lshrrev_b32_e32 v149, 4, v148
	v_and_b32_e32 v148, 15, v148
	v_lshlrev_b32_e32 v148, 4, v148
	v_lshl_add_u32 v148, v147, 10, v148
	v_max_u32_e32 v147, 3, v149
	v_mad_u32_u24 v137, v149, s87, v148
	v_mad_u32_u24 v144, v147, s87, v148
	v_add_u32_e32 v146, 0xc00, v242
	v_min_u32_e32 v146, 0xc8f, v146
	v_mul_hi_u32 v147, v146, s6
	v_lshrrev_b32_e32 v147, 5, v147
	v_mul_u32_u24_e32 v148, 0x430, v147
	v_sub_u32_e32 v148, v146, v148
	v_lshrrev_b32_e32 v149, 4, v148
	v_and_b32_e32 v148, 15, v148
	v_lshlrev_b32_e32 v148, 4, v148
	v_lshl_add_u32 v148, v147, 10, v148
	v_max_u32_e32 v147, 3, v149
	v_mad_u32_u24 v138, v149, s87, v148
	v_mad_u32_u24 v145, v147, s87, v148
	v_cmp_eq_u32_e64 s[6:7], 0, v224
	s_add_u32 s72, s78, 0x14000000
	s_waitcnt vmcnt(16)
	v_cndmask_b32_e64 v17, 0, v17, s[46:47]
	v_writelane_b32 v254, s6, 27
	v_cndmask_b32_e64 v16, 0, v16, s[46:47]
	v_cndmask_b32_e64 v15, 0, v15, s[46:47]
	v_writelane_b32 v254, s7, 28
	v_cmp_gt_u32_e64 s[6:7], 2, v224
	v_cndmask_b32_e64 v14, 0, v14, s[46:47]
	s_addc_u32 s46, s79, 0
	v_writelane_b32 v254, s6, 29
	v_cndmask_b32_e64 v9, 0, v9, s[42:43]
	v_cndmask_b32_e64 v8, 0, v8, s[42:43]
	v_writelane_b32 v254, s7, 30
	v_cmp_gt_u32_e64 s[6:7], 4, v224
	v_cndmask_b32_e64 v7, 0, v7, s[42:43]
	v_cndmask_b32_e64 v6, 0, v6, s[42:43]
	v_writelane_b32 v254, s6, 31
	v_cndmask_b32_e64 v5, 0, v5, s[44:45]
	v_cndmask_b32_e64 v4, 0, v4, s[44:45]
	v_writelane_b32 v254, s7, 32
	v_cmp_gt_u32_e64 s[6:7], 8, v224
	v_cndmask_b32_e64 v3, 0, v3, s[44:45]
	v_cndmask_b32_e64 v2, 0, v2, s[44:45]
	v_writelane_b32 v254, s6, 33
	s_waitcnt vmcnt(15)
	v_cndmask_b32_e64 v13, 0, v13, s[48:49]
	v_cndmask_b32_e64 v12, 0, v12, s[48:49]
	v_writelane_b32 v254, s7, 34
	v_cmp_gt_u32_e64 s[6:7], 16, v224
	v_cndmask_b32_e64 v11, 0, v11, s[48:49]
	v_cndmask_b32_e64 v10, 0, v10, s[48:49]
	v_writelane_b32 v254, s6, 35
	s_waitcnt vmcnt(14)
	v_cndmask_b32_e64 v25, 0, v25, s[50:51]
	v_cndmask_b32_e64 v24, 0, v24, s[50:51]
	v_writelane_b32 v254, s7, 36
	v_cmp_gt_u32_e64 s[6:7], 32, v224
	v_cndmask_b32_e64 v23, 0, v23, s[50:51]
	v_cndmask_b32_e64 v22, 0, v22, s[50:51]
	v_writelane_b32 v254, s6, 37
	s_waitcnt vmcnt(13)
	v_cndmask_b32_e64 v21, 0, v21, s[52:53]
	v_cndmask_b32_e64 v20, 0, v20, s[52:53]
	v_cndmask_b32_e64 v19, 0, v19, s[52:53]
	v_cndmask_b32_e64 v18, 0, v18, s[52:53]
	s_waitcnt vmcnt(12)
	v_cndmask_b32_e64 v29, 0, v29, s[54:55]
	v_cndmask_b32_e64 v28, 0, v28, s[54:55]
	v_cndmask_b32_e64 v27, 0, v27, s[54:55]
	v_cndmask_b32_e64 v26, 0, v26, s[54:55]
	s_and_b32 s73, s46, 0xffff
	v_lshl_add_u64 v[70:71], s[28:29], 0, v[130:131]
	v_writelane_b32 v254, s7, 38
	s_mov_b32 s34, -1
	v_readlane_b32 s50, v250, 18

.LBB0_133:
	s_or_b64 exec, exec, s[28:29]
	s_add_i32 s47, s50, s5
	s_cmpk_gt_i32 s47, 0x7ff
	s_cselect_b64 s[44:45], -1, 0
	s_lshl_b32 s6, s47, 6
	s_and_b32 s6, s6, 0x7c0
	s_ashr_i32 s7, s47, 5
	s_or_b32 s6, s6, s7
	s_cmpk_lt_i32 s47, 0x800
	s_cselect_b32 s7, s6, s42
	s_and_b32 s10, s7, 63
	s_lshl_b32 s6, s7, 4
	s_lshl_b32 s8, s7, 2
	s_and_b32 s6, s6, 0xfffff000
	s_lshl_b32 s11, s10, 6
	s_and_b32 s8, s8, 0x300
	s_add_u32 s8, s88, s8
	s_addc_u32 s9, s89, 0
	s_cmp_lg_u32 s10, 0
	s_cselect_b64 s[28:29], -1, 0
	s_or_b32 s10, s11, s6
	s_add_i32 s10, s10, -3
	s_mul_i32 s11, s10, 0x1800
	s_mul_hi_i32 s34, s10, 0x1800
	s_add_u32 s8, s8, s11
	s_addc_u32 s9, s9, s34
	v_cmp_eq_u32_e64 s[56:57], v132, v139
	v_cmp_eq_u32_e64 s[58:59], v133, v140
	v_cmp_eq_u32_e64 s[60:61], v134, v141
	v_cmp_eq_u32_e64 s[62:63], v135, v142
	v_cmp_eq_u32_e64 s[64:65], v136, v143
	v_cmp_eq_u32_e64 s[66:67], v137, v144
	v_cmp_eq_u32_e64 s[68:69], v138, v145
	s_or_b64 s[56:57], s[56:57], s[28:29]
	s_or_b64 s[58:59], s[58:59], s[28:29]
	s_or_b64 s[60:61], s[60:61], s[28:29]
	s_or_b64 s[62:63], s[62:63], s[28:29]
	s_or_b64 s[64:65], s[64:65], s[28:29]
	s_or_b64 s[66:67], s[66:67], s[28:29]
	s_or_b64 s[68:69], s[68:69], s[28:29]
	v_cndmask_b32_e64 v2, v139, v132, s[56:57]
	v_cndmask_b32_e64 v3, v140, v133, s[58:59]
	v_cndmask_b32_e64 v4, v141, v134, s[60:61]
	v_cndmask_b32_e64 v5, v142, v135, s[62:63]
	v_cndmask_b32_e64 v6, v143, v136, s[64:65]
	v_cndmask_b32_e64 v7, v144, v137, s[66:67]
	v_cndmask_b32_e64 v8, v145, v138, s[68:69]
	global_load_dwordx4 v[38:41], v2, s[8:9]
	global_load_dwordx4 v[34:37], v3, s[8:9]
	global_load_dwordx4 v[46:49], v4, s[8:9]
	global_load_dwordx4 v[42:45], v5, s[8:9]
	global_load_dwordx4 v[54:57], v6, s[8:9]
	global_load_dwordx4 v[50:53], v7, s[8:9]
	global_load_dwordx4 v[58:61], v8, s[8:9]
	s_bfe_u32 s28, s7, 0x20006
	s_lshl_b32 s34, s28, 9
	v_lshl_add_u64 v[2:3], v[70:71], 0, s[34:35]
	v_add_co_u32_e32 v4, vcc, s90, v2
	s_movk_i32 s8, 0x3000
	s_nop 0
	v_addc_co_u32_e32 v5, vcc, 0, v3, vcc
	v_add_co_u32_e32 v6, vcc, s8, v2
	s_movk_i32 s8, 0x2000
	s_nop 0
	v_addc_co_u32_e32 v7, vcc, 0, v3, vcc
	v_add_co_u32_e32 v8, vcc, s97, v2
	s_lshl_b32 s7, s7, 6
	s_nop 0
	v_addc_co_u32_e32 v9, vcc, 0, v3, vcc
	v_add_co_u32_e32 v10, vcc, s8, v2
	s_movk_i32 s8, 0x5000
	s_nop 0
	v_addc_co_u32_e32 v11, vcc, 0, v3, vcc
	s_and_b32 s7, s7, 0xfc0
	v_add_co_u32_e32 v12, vcc, s8, v2
	s_lshl_b32 s34, s28, 2
	s_nop 0
	v_addc_co_u32_e32 v13, vcc, 0, v3, vcc
	global_load_dwordx2 v[74:75], v[10:11], off
	global_load_dwordx2 v[76:77], v[12:13], off
	global_load_dwordx2 v[64:65], v[10:11], off offset:2048
	global_load_dwordx2 v[78:79], v[6:7], off offset:2048
	global_load_dwordx2 v[86:87], v[2:3], off
	global_load_dwordx2 v[84:85], v[4:5], off offset:2048
	global_load_dwordx2 v[72:73], v[2:3], off offset:2048
	global_load_dwordx2 v[66:67], v[4:5], off
	global_load_dwordx2 v[80:81], v[8:9], off offset:-4096
	global_load_dwordx2 v[82:83], v[8:9], off offset:2048
	global_load_dwordx2 v[62:63], v[8:9], off
	global_load_dwordx2 v[68:69], v[12:13], off offset:2048
	v_or_b32_e32 v2, s7, v224
	v_or_b32_e32 v2, s6, v2
	v_ashrrev_i32_e32 v3, 31, v2
	v_readlane_b32 s6, v254, 22
	s_load_dwordx4 s[8:11], s[0:1], 0x60
	v_lshlrev_b64 v[2:3], 5, v[2:3]
	v_readlane_b32 s7, v254, 23
	s_nop 1
	v_lshl_add_u64 v[2:3], s[6:7], 0, v[2:3]
	s_or_b32 s6, s28, s18
	s_ashr_i32 s7, s6, 31
	s_lshl_b64 s[6:7], s[6:7], 2
	s_waitcnt lgkmcnt(0)
	s_add_u32 s10, s10, s6
	s_addc_u32 s11, s11, s7
	s_add_u32 s6, s8, s6
	v_lshl_add_u64 v[2:3], v[2:3], 0, s[34:35]
	s_addc_u32 s7, s9, s7
	s_lshl_b32 s34, s48, 10
	global_load_dword v99, v[2:3], off
	global_load_dword v98, v[2:3], off offset:16
	v_or_b32_e32 v2, s34, v93
	v_lshl_add_u32 v95, v2, 2, 0
	global_load_dword v100, v131, s[10:11]
	global_load_dword v97, v131, s[6:7]
	ds_read2st64_b32 v[30:31], v95 offset1:1
	ds_read2st64_b32 v[26:27], v95 offset0:128 offset1:129
	ds_read2st64_b32 v[28:29], v95 offset0:2 offset1:3
	ds_read2st64_b32 v[24:25], v95 offset0:4 offset1:5
	ds_read2st64_b32 v[22:23], v95 offset0:6 offset1:7
	ds_read2st64_b32 v[32:33], v95 offset0:130 offset1:131
	ds_read2st64_b32 v[20:21], v95 offset0:132 offset1:133
	ds_read2st64_b32 v[18:19], v95 offset0:134 offset1:135
	s_waitcnt lgkmcnt(6)
	v_pk_mul_f32 v[2:3], v[26:27], v[26:27]
	ds_read2st64_b32 v[14:15], v95 offset0:8 offset1:9
	ds_read2st64_b32 v[10:11], v95 offset0:136 offset1:137
	ds_read2st64_b32 v[12:13], v95 offset0:10 offset1:11
	ds_read2st64_b32 v[8:9], v95 offset0:12 offset1:13
	ds_read2st64_b32 v[6:7], v95 offset0:14 offset1:15
	v_add_f32_e32 v101, v2, v3
	s_waitcnt lgkmcnt(7)
	v_pk_mul_f32 v[2:3], v[32:33], v[32:33]
	v_mul_f32_e32 v96, v31, v31
	v_add_f32_e32 v105, v2, v3
	s_waitcnt lgkmcnt(6)
	v_pk_mul_f32 v[2:3], v[20:21], v[20:21]
	v_fmac_f32_e32 v96, v30, v30
	v_add_f32_e32 v107, v2, v3
	s_waitcnt lgkmcnt(5)
	v_pk_mul_f32 v[2:3], v[18:19], v[18:19]
	s_waitcnt lgkmcnt(3)
	v_pk_mul_f32 v[102:103], v[10:11], v[10:11]
	v_add_f32_e32 v109, v2, v3
	ds_read2st64_b32 v[16:17], v95 offset0:138 offset1:139
	ds_read2st64_b32 v[4:5], v95 offset0:140 offset1:141
	ds_read2st64_b32 v[2:3], v95 offset0:142 offset1:143
	v_add_f32_e32 v111, v102, v103
	v_add_f32_dpp v96, v96, v96 quad_perm:[1,0,3,2] row_mask:0xf bank_mask:0xf bound_ctrl:1
	s_waitcnt lgkmcnt(2)
	v_pk_mul_f32 v[102:103], v[16:17], v[16:17]
	v_mul_f32_e32 v104, v29, v29
	v_mul_f32_e32 v106, v25, v25
	v_mul_f32_e32 v108, v23, v23
	v_mul_f32_e32 v110, v15, v15
	v_mul_f32_e32 v112, v13, v13
	v_add_f32_e32 v113, v102, v103
	v_mul_f32_e32 v114, v9, v9
	s_waitcnt lgkmcnt(1)
	v_pk_mul_f32 v[102:103], v[4:5], v[4:5]
	v_mul_f32_e32 v116, v7, v7
	v_add_f32_dpp v96, v96, v96 quad_perm:[2,3,0,1] row_mask:0xf bank_mask:0xf bound_ctrl:1
	v_fmac_f32_e32 v104, v28, v28
	v_fmac_f32_e32 v106, v24, v24
	v_fmac_f32_e32 v108, v22, v22
	v_fmac_f32_e32 v110, v14, v14
	v_fmac_f32_e32 v112, v12, v12
	v_fmac_f32_e32 v114, v8, v8
	v_add_f32_e32 v115, v102, v103
	v_fmac_f32_e32 v116, v6, v6
	s_waitcnt lgkmcnt(0)
	v_pk_mul_f32 v[102:103], v[2:3], v[2:3]
	v_add_f32_dpp v101, v101, v101 quad_perm:[1,0,3,2] row_mask:0xf bank_mask:0xf bound_ctrl:1
	v_add_f32_dpp v96, v96, v96 row_half_mirror row_mask:0xf bank_mask:0xf bound_ctrl:1
	v_add_f32_e32 v102, v102, v103
	v_add_f32_dpp v103, v104, v104 quad_perm:[1,0,3,2] row_mask:0xf bank_mask:0xf bound_ctrl:1
	v_add_f32_dpp v104, v105, v105 quad_perm:[1,0,3,2] row_mask:0xf bank_mask:0xf bound_ctrl:1
	v_add_f32_dpp v105, v106, v106 quad_perm:[1,0,3,2] row_mask:0xf bank_mask:0xf bound_ctrl:1
	v_add_f32_dpp v106, v107, v107 quad_perm:[1,0,3,2] row_mask:0xf bank_mask:0xf bound_ctrl:1
	v_add_f32_dpp v107, v108, v108 quad_perm:[1,0,3,2] row_mask:0xf bank_mask:0xf bound_ctrl:1
	v_add_f32_dpp v108, v109, v109 quad_perm:[1,0,3,2] row_mask:0xf bank_mask:0xf bound_ctrl:1
	v_add_f32_dpp v109, v110, v110 quad_perm:[1,0,3,2] row_mask:0xf bank_mask:0xf bound_ctrl:1
	v_add_f32_dpp v110, v111, v111 quad_perm:[1,0,3,2] row_mask:0xf bank_mask:0xf bound_ctrl:1
	v_add_f32_dpp v111, v112, v112 quad_perm:[1,0,3,2] row_mask:0xf bank_mask:0xf bound_ctrl:1
	v_add_f32_dpp v112, v113, v113 quad_perm:[1,0,3,2] row_mask:0xf bank_mask:0xf bound_ctrl:1
	v_add_f32_dpp v113, v114, v114 quad_perm:[1,0,3,2] row_mask:0xf bank_mask:0xf bound_ctrl:1
	v_add_f32_dpp v114, v115, v115 quad_perm:[1,0,3,2] row_mask:0xf bank_mask:0xf bound_ctrl:1
	v_add_f32_dpp v115, v116, v116 quad_perm:[1,0,3,2] row_mask:0xf bank_mask:0xf bound_ctrl:1
	v_add_f32_dpp v101, v101, v101 quad_perm:[2,3,0,1] row_mask:0xf bank_mask:0xf bound_ctrl:1
	v_add_f32_dpp v96, v96, v96 row_mirror row_mask:0xf bank_mask:0xf bound_ctrl:1
	v_mov_b32_e32 v116, v131
	v_add_f32_dpp v101, v101, v101 row_half_mirror row_mask:0xf bank_mask:0xf bound_ctrl:1
	v_add_f32_dpp v103, v103, v103 quad_perm:[2,3,0,1] row_mask:0xf bank_mask:0xf bound_ctrl:1
	v_mov_b32_dpp v116, v96 row_bcast:15 row_mask:0xa bank_mask:0xf
	v_add_f32_dpp v101, v101, v101 row_mirror row_mask:0xf bank_mask:0xf bound_ctrl:1
	v_add_f32_e32 v96, v96, v116
	v_mov_b32_e32 v116, v131
	v_add_f32_dpp v103, v103, v103 row_half_mirror row_mask:0xf bank_mask:0xf bound_ctrl:1
	v_add_f32_dpp v104, v104, v104 quad_perm:[2,3,0,1] row_mask:0xf bank_mask:0xf bound_ctrl:1
	v_mov_b32_dpp v116, v101 row_bcast:15 row_mask:0xa bank_mask:0xf
	v_add_f32_dpp v103, v103, v103 row_mirror row_mask:0xf bank_mask:0xf bound_ctrl:1
	v_add_f32_e32 v101, v101, v116
	v_mov_b32_e32 v116, v131
	v_add_f32_dpp v104, v104, v104 row_half_mirror row_mask:0xf bank_mask:0xf bound_ctrl:1
	v_add_f32_dpp v105, v105, v105 quad_perm:[2,3,0,1] row_mask:0xf bank_mask:0xf bound_ctrl:1
	v_mov_b32_dpp v116, v103 row_bcast:15 row_mask:0xa bank_mask:0xf
	v_add_f32_dpp v104, v104, v104 row_mirror row_mask:0xf bank_mask:0xf bound_ctrl:1
	v_add_f32_e32 v103, v103, v116
	v_mov_b32_e32 v116, v131
	v_add_f32_dpp v105, v105, v105 row_half_mirror row_mask:0xf bank_mask:0xf bound_ctrl:1
	v_add_f32_dpp v106, v106, v106 quad_perm:[2,3,0,1] row_mask:0xf bank_mask:0xf bound_ctrl:1
	v_mov_b32_dpp v116, v104 row_bcast:15 row_mask:0xa bank_mask:0xf
	v_add_f32_dpp v105, v105, v105 row_mirror row_mask:0xf bank_mask:0xf bound_ctrl:1
	v_add_f32_e32 v104, v104, v116
	v_mov_b32_e32 v116, v131
	v_add_f32_dpp v106, v106, v106 row_half_mirror row_mask:0xf bank_mask:0xf bound_ctrl:1
	v_add_f32_dpp v107, v107, v107 quad_perm:[2,3,0,1] row_mask:0xf bank_mask:0xf bound_ctrl:1
	v_mov_b32_dpp v116, v105 row_bcast:15 row_mask:0xa bank_mask:0xf
	v_add_f32_dpp v106, v106, v106 row_mirror row_mask:0xf bank_mask:0xf bound_ctrl:1
	v_add_f32_e32 v105, v105, v116
	v_mov_b32_e32 v116, v131
	v_add_f32_dpp v107, v107, v107 row_half_mirror row_mask:0xf bank_mask:0xf bound_ctrl:1
	v_add_f32_dpp v108, v108, v108 quad_perm:[2,3,0,1] row_mask:0xf bank_mask:0xf bound_ctrl:1
	v_mov_b32_dpp v116, v106 row_bcast:15 row_mask:0xa bank_mask:0xf
	v_add_f32_dpp v107, v107, v107 row_mirror row_mask:0xf bank_mask:0xf bound_ctrl:1
	v_add_f32_e32 v106, v106, v116
	v_mov_b32_e32 v116, v131
	v_add_f32_dpp v108, v108, v108 row_half_mirror row_mask:0xf bank_mask:0xf bound_ctrl:1
	v_add_f32_dpp v109, v109, v109 quad_perm:[2,3,0,1] row_mask:0xf bank_mask:0xf bound_ctrl:1
	v_mov_b32_dpp v116, v107 row_bcast:15 row_mask:0xa bank_mask:0xf
	v_add_f32_dpp v108, v108, v108 row_mirror row_mask:0xf bank_mask:0xf bound_ctrl:1
	v_add_f32_e32 v107, v107, v116
	v_mov_b32_e32 v116, v131
	v_add_f32_dpp v109, v109, v109 row_half_mirror row_mask:0xf bank_mask:0xf bound_ctrl:1
	v_add_f32_dpp v110, v110, v110 quad_perm:[2,3,0,1] row_mask:0xf bank_mask:0xf bound_ctrl:1
	v_mov_b32_dpp v116, v108 row_bcast:15 row_mask:0xa bank_mask:0xf
	v_add_f32_dpp v109, v109, v109 row_mirror row_mask:0xf bank_mask:0xf bound_ctrl:1
	v_add_f32_e32 v108, v108, v116
	v_mov_b32_e32 v116, v131
	v_add_f32_dpp v110, v110, v110 row_half_mirror row_mask:0xf bank_mask:0xf bound_ctrl:1
	v_add_f32_dpp v111, v111, v111 quad_perm:[2,3,0,1] row_mask:0xf bank_mask:0xf bound_ctrl:1
	v_mov_b32_dpp v116, v109 row_bcast:15 row_mask:0xa bank_mask:0xf
	v_add_f32_dpp v110, v110, v110 row_mirror row_mask:0xf bank_mask:0xf bound_ctrl:1
	v_add_f32_e32 v109, v109, v116
	v_mov_b32_e32 v116, v131
	v_add_f32_dpp v111, v111, v111 row_half_mirror row_mask:0xf bank_mask:0xf bound_ctrl:1
	v_add_f32_dpp v112, v112, v112 quad_perm:[2,3,0,1] row_mask:0xf bank_mask:0xf bound_ctrl:1
	v_mov_b32_dpp v116, v110 row_bcast:15 row_mask:0xa bank_mask:0xf
	v_add_f32_dpp v111, v111, v111 row_mirror row_mask:0xf bank_mask:0xf bound_ctrl:1
	v_add_f32_e32 v110, v110, v116
	v_mov_b32_e32 v116, v131
	v_add_f32_dpp v112, v112, v112 row_half_mirror row_mask:0xf bank_mask:0xf bound_ctrl:1
	v_add_f32_dpp v113, v113, v113 quad_perm:[2,3,0,1] row_mask:0xf bank_mask:0xf bound_ctrl:1
	v_mov_b32_dpp v116, v111 row_bcast:15 row_mask:0xa bank_mask:0xf
	v_add_f32_dpp v112, v112, v112 row_mirror row_mask:0xf bank_mask:0xf bound_ctrl:1
	v_add_f32_e32 v111, v111, v116
	v_mov_b32_e32 v116, v131
	v_add_f32_dpp v113, v113, v113 row_half_mirror row_mask:0xf bank_mask:0xf bound_ctrl:1
	v_add_f32_dpp v114, v114, v114 quad_perm:[2,3,0,1] row_mask:0xf bank_mask:0xf bound_ctrl:1
	v_mov_b32_dpp v116, v112 row_bcast:15 row_mask:0xa bank_mask:0xf
	v_add_f32_dpp v113, v113, v113 row_mirror row_mask:0xf bank_mask:0xf bound_ctrl:1
	v_add_f32_e32 v112, v112, v116
	v_mov_b32_e32 v116, v131
	v_add_f32_dpp v114, v114, v114 row_half_mirror row_mask:0xf bank_mask:0xf bound_ctrl:1
	v_add_f32_dpp v115, v115, v115 quad_perm:[2,3,0,1] row_mask:0xf bank_mask:0xf bound_ctrl:1
	v_mov_b32_dpp v116, v113 row_bcast:15 row_mask:0xa bank_mask:0xf
	v_add_f32_dpp v114, v114, v114 row_mirror row_mask:0xf bank_mask:0xf bound_ctrl:1
	v_add_f32_e32 v113, v113, v116
	v_mov_b32_e32 v116, v131
	v_add_f32_dpp v102, v102, v102 quad_perm:[1,0,3,2] row_mask:0xf bank_mask:0xf bound_ctrl:1
	v_add_f32_dpp v115, v115, v115 row_half_mirror row_mask:0xf bank_mask:0xf bound_ctrl:1
	v_mov_b32_dpp v116, v114 row_bcast:15 row_mask:0xa bank_mask:0xf
	v_add_f32_dpp v102, v102, v102 quad_perm:[2,3,0,1] row_mask:0xf bank_mask:0xf bound_ctrl:1
	v_add_f32_dpp v115, v115, v115 row_mirror row_mask:0xf bank_mask:0xf bound_ctrl:1
	v_add_f32_e32 v114, v114, v116
	v_mov_b32_e32 v116, v131
	v_add_f32_dpp v102, v102, v102 row_half_mirror row_mask:0xf bank_mask:0xf bound_ctrl:1
	s_lshl_b32 vcc_hi, s48, 3
	v_mov_b32_dpp v116, v115 row_bcast:15 row_mask:0xa bank_mask:0xf
	v_add_f32_dpp v102, v102, v102 row_mirror row_mask:0xf bank_mask:0xf bound_ctrl:1
	v_add_f32_e32 v115, v115, v116
	v_mov_b32_e32 v116, v131
	s_nop 1
	v_mov_b32_dpp v116, v102 row_bcast:15 row_mask:0xa bank_mask:0xf
	v_add_f32_e32 v102, v102, v116
	v_mov_b32_e32 v116, v131
	s_nop 1
	v_mov_b32_dpp v116, v96 row_bcast:31 row_mask:0xc bank_mask:0xf
	v_add_f32_e32 v96, v96, v116
	v_mov_b32_e32 v116, v131
	v_readlane_b32 s7, v96, 63
	s_nop 0
	v_mov_b32_dpp v116, v101 row_bcast:31 row_mask:0xc bank_mask:0xf
	v_add_f32_e32 v101, v101, v116
	v_mov_b32_e32 v116, v131
	v_add_f32_e32 v96, s7, v225
	v_rsq_f32_e32 v96, v96
	v_mov_b32_dpp v116, v103 row_bcast:31 row_mask:0xc bank_mask:0xf
	v_add_f32_e32 v103, v103, v116
	v_mov_b32_e32 v116, v131
	v_readlane_b32 s8, v101, 63
	v_mul_f32_e32 v96, 0x3db504f3, v96
	v_mov_b32_dpp v116, v104 row_bcast:31 row_mask:0xc bank_mask:0xf
	v_add_f32_e32 v104, v104, v116
	v_mov_b32_e32 v116, v131
	v_mul_f32_e32 v30, v30, v96
	v_mul_f32_e32 v31, v31, v96
	v_mov_b32_dpp v116, v105 row_bcast:31 row_mask:0xc bank_mask:0xf
	v_add_f32_e32 v105, v105, v116
	v_mov_b32_e32 v116, v131
	v_readlane_b32 s9, v103, 63
	v_or_b32_e32 v101, 64, v93
	v_mov_b32_dpp v116, v106 row_bcast:31 row_mask:0xc bank_mask:0xf
	v_add_f32_e32 v106, v106, v116
	v_mov_b32_e32 v116, v131
	ds_write2st64_b32 v95, v30, v31 offset1:1
	v_cvt_pk_bf16_f32 v30, v30, s0
	v_mov_b32_dpp v116, v107 row_bcast:31 row_mask:0xc bank_mask:0xf
	v_add_f32_e32 v107, v107, v116
	v_mov_b32_e32 v116, v131
	v_readlane_b32 s10, v104, 63
	v_readlane_b32 s11, v105, 63
	v_mov_b32_dpp v116, v108 row_bcast:31 row_mask:0xc bank_mask:0xf
	v_add_f32_e32 v108, v108, v116
	v_mov_b32_e32 v116, v131
	v_readlane_b32 s40, v107, 63
	v_readlane_b32 s29, v106, 63
	v_mov_b32_dpp v116, v109 row_bcast:31 row_mask:0xc bank_mask:0xf
	v_add_f32_e32 v109, v109, v116
	v_mov_b32_e32 v116, v131
	v_readlane_b32 s41, v108, 63
	v_readlane_b32 s52, v109, 63
	v_mov_b32_dpp v116, v110 row_bcast:31 row_mask:0xc bank_mask:0xf
	v_add_f32_e32 v110, v110, v116
	v_mov_b32_e32 v116, v131
	v_readlane_b32 s53, v110, 63
	s_nop 0
	v_mov_b32_dpp v116, v111 row_bcast:31 row_mask:0xc bank_mask:0xf
	v_add_f32_e32 v111, v111, v116
	v_mov_b32_e32 v116, v131
	v_readlane_b32 s84, v111, 63
	s_nop 0
	v_mov_b32_dpp v116, v112 row_bcast:31 row_mask:0xc bank_mask:0xf
	v_add_f32_e32 v112, v112, v116
	v_mov_b32_e32 v116, v131
	v_readlane_b32 s85, v112, 63
	s_nop 0
	v_mov_b32_dpp v116, v113 row_bcast:31 row_mask:0xc bank_mask:0xf
	v_add_f32_e32 v113, v113, v116
	v_mov_b32_e32 v116, v131
	v_readlane_b32 vcc_lo, v113, 63
	s_nop 0
	v_mov_b32_dpp v116, v114 row_bcast:31 row_mask:0xc bank_mask:0xf
	v_add_f32_e32 v114, v114, v116
	v_mov_b32_e32 v116, v131
	v_readlane_b32 s28, v114, 63
	s_nop 0
	v_mov_b32_dpp v116, v115 row_bcast:31 row_mask:0xc bank_mask:0xf
	v_add_f32_e32 v115, v115, v116
	v_mov_b32_e32 v116, v131
	v_readlane_b32 s6, v115, 63
	s_nop 0
	v_mov_b32_dpp v116, v102 row_bcast:31 row_mask:0xc bank_mask:0xf
	v_add_f32_e32 v102, v102, v116
	s_nop 0
	v_readlane_b32 s7, v102, 63
	v_add_f32_e32 v102, s8, v225
	s_mul_i32 s8, s48, 0x440
	v_or_b32_e32 v96, s8, v93
	v_lshlrev_b32_e32 v96, 1, v96
	v_add_u32_e32 v103, s49, v96
	ds_write_b16 v103, v30
	v_cvt_pk_bf16_f32 v30, v31, s0
	v_add_lshl_u32 v31, v101, s8, 1
	v_add_u32_e32 v103, s49, v31
	ds_write_b16 v103, v30
	v_add_f32_e32 v30, s9, v225
	v_rsq_f32_e32 v30, v30
	v_add_f32_e32 v103, s10, v225
	v_rsq_f32_e32 v102, v102
	v_rsq_f32_e32 v103, v103
	v_mul_f32_e32 v30, 0x3db504f3, v30
	v_mul_f32_e32 v104, v28, v30
	v_mul_f32_e32 v30, v29, v30
	v_mov_b32_e32 v28, v26
	v_mov_b32_e32 v29, v32
	v_pk_mul_f32 v[28:29], v[28:29], v[102:103]
	v_add_u32_e32 v96, s91, v96
	v_cvt_pk_bf16_f32 v26, v28, s0
	v_mov_b32_e32 v32, v27
	ds_write_b16 v96, v26
	v_pk_mul_f32 v[26:27], v[32:33], v[102:103]
	v_add_u32_e32 v31, s91, v31
	s_or_b32 s8, vcc_hi, 1
	v_cvt_pk_bf16_f32 v32, v26, s0
	ds_write_b16 v31, v32
	v_lshl_or_b32 v31, s8, 9, v94
	s_mulk_i32 s8, 0x88
	v_add_u32_e32 v31, 0, v31
	v_add_lshl_u32 v32, s8, v93, 1
	ds_write2st64_b32 v95, v28, v26 offset0:128 offset1:129
	ds_write2st64_b32 v31, v104, v30 offset1:1
	ds_write2st64_b32 v31, v29, v27 offset0:128 offset1:129
	v_cvt_pk_bf16_f32 v31, v104, s0
	v_add_u32_e32 v33, s49, v32
	ds_write_b16 v33, v31
	v_add_lshl_u32 v31, s8, v101, 1
	v_cvt_pk_bf16_f32 v30, v30, s0
	v_add_u32_e32 v33, s49, v31
	ds_write_b16 v33, v30
	v_cvt_pk_bf16_f32 v30, v29, s0
	v_add_u32_e32 v32, s91, v32
	ds_write_b16 v32, v30
	v_add_f32_e32 v30, s11, v225
	v_rsq_f32_e32 v30, v30
	v_cvt_pk_bf16_f32 v32, v27, s0
	v_add_u32_e32 v31, s91, v31
	ds_write_b16 v31, v32
	v_mul_f32_e32 v31, 0x3db504f3, v30
	v_mul_f32_e32 v24, v24, v31
	v_mul_f32_e32 v25, v25, v31
	v_lshl_or_b32 v31, s48, 12, v94
	s_add_i32 s9, s8, 0x88
	v_add_u32_e32 v32, 0, v31
	v_add_lshl_u32 v31, s9, v93, 1
	ds_write2st64_b32 v32, v24, v25 offset0:4 offset1:5
	v_cvt_pk_bf16_f32 v24, v24, s0
	v_add_u32_e32 v33, s49, v31
	ds_write_b16 v33, v24
	v_cvt_pk_bf16_f32 v24, v25, s0
	v_add_lshl_u32 v25, s9, v101, 1
	v_add_f32_e32 v94, s40, v225
	v_add_u32_e32 v33, s49, v25
	v_rsq_f32_e32 v94, v94
	v_add_f32_e32 v30, s29, v225
	ds_write_b16 v33, v24
	v_add_u32_e32 v24, s91, v31
	v_add_f32_e32 v31, s41, v225
	v_rsq_f32_e32 v30, v30
	v_rsq_f32_e32 v31, v31
	v_mul_f32_e32 v33, 0x3db504f3, v94
	v_mul_f32_e32 v94, v22, v33
	v_mul_f32_e32 v33, v23, v33
	v_mov_b32_e32 v22, v20
	v_mov_b32_e32 v23, v18
	v_pk_mul_f32 v[22:23], v[22:23], v[30:31]
	s_add_i32 s9, s8, 0x110
	v_cvt_pk_bf16_f32 v18, v22, s0
	ds_write_b16 v24, v18
	v_mov_b32_e32 v18, v21
	v_pk_mul_f32 v[18:19], v[18:19], v[30:31]
	v_add_u32_e32 v25, s91, v25
	v_cvt_pk_bf16_f32 v20, v18, s0
	v_add_lshl_u32 v21, s9, v93, 1
	ds_write2st64_b32 v32, v22, v18 offset0:132 offset1:133
	ds_write_b16 v25, v20
	ds_write2st64_b32 v32, v94, v33 offset0:6 offset1:7
	ds_write2st64_b32 v32, v23, v19 offset0:134 offset1:135
	v_cvt_pk_bf16_f32 v20, v94, s0
	v_add_u32_e32 v24, s49, v21
	ds_write_b16 v24, v20
	v_add_lshl_u32 v24, s9, v101, 1
	v_cvt_pk_bf16_f32 v20, v33, s0
	v_add_u32_e32 v25, s49, v24
	ds_write_b16 v25, v20
	v_cvt_pk_bf16_f32 v20, v23, s0
	v_add_u32_e32 v21, s91, v21
	ds_write_b16 v21, v20
	v_add_f32_e32 v20, s52, v225
	v_rsq_f32_e32 v20, v20
	v_cvt_pk_bf16_f32 v21, v19, s0
	v_add_u32_e32 v24, s91, v24
	ds_write_b16 v24, v21
	v_mul_f32_e32 v21, 0x3db504f3, v20
	s_add_i32 s9, s8, 0x198
	v_mul_f32_e32 v14, v14, v21
	v_mul_f32_e32 v15, v15, v21
	v_add_lshl_u32 v21, s9, v93, 1
	ds_write2st64_b32 v32, v14, v15 offset0:8 offset1:9
	v_cvt_pk_bf16_f32 v14, v14, s0
	v_add_u32_e32 v24, s49, v21
	ds_write_b16 v24, v14
	v_cvt_pk_bf16_f32 v14, v15, s0
	v_add_lshl_u32 v15, s9, v101, 1
	v_add_f32_e32 v25, s84, v225
	v_add_u32_e32 v24, s49, v15
	v_rsq_f32_e32 v25, v25
	v_add_f32_e32 v20, s53, v225
	ds_write_b16 v24, v14
	v_add_u32_e32 v14, s91, v21
	v_add_f32_e32 v21, s85, v225
	v_rsq_f32_e32 v20, v20
	v_rsq_f32_e32 v21, v21
	v_mul_f32_e32 v24, 0x3db504f3, v25
	v_mul_f32_e32 v25, v12, v24
	v_mul_f32_e32 v24, v13, v24
	v_mov_b32_e32 v12, v10
	v_mov_b32_e32 v13, v16
	v_pk_mul_f32 v[12:13], v[12:13], v[20:21]
	v_mov_b32_e32 v16, v11
	v_cvt_pk_bf16_f32 v10, v12, s0
	ds_write_b16 v14, v10
	v_pk_mul_f32 v[10:11], v[16:17], v[20:21]
	v_add_u32_e32 v15, s91, v15
	v_cvt_pk_bf16_f32 v14, v10, s0
	s_add_i32 s9, s8, 0x220
	ds_write2st64_b32 v32, v12, v10 offset0:136 offset1:137
	ds_write_b16 v15, v14
	ds_write2st64_b32 v32, v25, v24 offset0:10 offset1:11
	ds_write2st64_b32 v32, v13, v11 offset0:138 offset1:139
	v_add_lshl_u32 v15, s9, v93, 1
	v_cvt_pk_bf16_f32 v14, v25, s0
	v_add_u32_e32 v16, s49, v15
	ds_write_b16 v16, v14
	v_add_lshl_u32 v16, s9, v101, 1
	v_cvt_pk_bf16_f32 v14, v24, s0
	v_add_u32_e32 v17, s49, v16
	ds_write_b16 v17, v14
	v_cvt_pk_bf16_f32 v14, v13, s0
	v_add_u32_e32 v15, s91, v15
	ds_write_b16 v15, v14
	v_add_f32_e32 v14, vcc_lo, v225
	v_rsq_f32_e32 v14, v14
	v_cvt_pk_bf16_f32 v15, v11, s0
	v_add_u32_e32 v16, s91, v16
	ds_write_b16 v16, v15
	v_mul_f32_e32 v15, 0x3db504f3, v14
	s_add_i32 s9, s8, 0x2a8
	v_mul_f32_e32 v8, v8, v15
	v_mul_f32_e32 v9, v9, v15
	v_add_lshl_u32 v15, s9, v93, 1
	ds_write2st64_b32 v32, v8, v9 offset0:12 offset1:13
	v_cvt_pk_bf16_f32 v8, v8, s0
	v_add_u32_e32 v16, s49, v15
	ds_write_b16 v16, v8
	v_cvt_pk_bf16_f32 v8, v9, s0
	v_add_lshl_u32 v9, s9, v101, 1
	v_add_f32_e32 v17, s6, v225
	v_add_u32_e32 v16, s49, v9
	v_rsq_f32_e32 v17, v17
	v_add_f32_e32 v14, s28, v225
	ds_write_b16 v16, v8
	v_add_u32_e32 v8, s91, v15
	v_add_f32_e32 v15, s7, v225
	v_rsq_f32_e32 v14, v14
	v_rsq_f32_e32 v15, v15
	v_add_u32_e32 v16, s91, v9
	v_mul_f32_e32 v9, 0x3db504f3, v17
	v_mul_f32_e32 v17, v6, v9
	v_mul_f32_e32 v20, v7, v9
	v_mov_b32_e32 v6, v4
	v_mov_b32_e32 v7, v2
	v_pk_mul_f32 v[6:7], v[6:7], v[14:15]
	s_addk_i32 s8, 0x330
	v_cvt_pk_bf16_f32 v2, v6, s0
	ds_write_b16 v8, v2
	v_mov_b32_e32 v2, v5
	v_pk_mul_f32 v[8:9], v[2:3], v[14:15]
	v_add_lshl_u32 v3, s8, v93, 1
	v_cvt_pk_bf16_f32 v2, v8, s0
	ds_write2st64_b32 v32, v6, v8 offset0:140 offset1:141
	ds_write_b16 v16, v2
	ds_write2st64_b32 v32, v17, v20 offset0:14 offset1:15
	ds_write2st64_b32 v32, v7, v9 offset0:142 offset1:143
	v_cvt_pk_bf16_f32 v2, v17, s0
	v_add_u32_e32 v4, s49, v3
	ds_write_b16 v4, v2
	v_add_lshl_u32 v4, s8, v101, 1
	v_cvt_pk_bf16_f32 v2, v20, s0
	v_add_u32_e32 v5, s49, v4
	ds_write_b16 v5, v2
	v_cvt_pk_bf16_f32 v5, v6, v7
	v_bitop3_b32 v6, s48, v1, 7 bitop3:0x78
	v_cvt_pk_bf16_f32 v2, v7, s0
	v_lshlrev_b32_e32 v7, 7, v93
	s_add_i32 s6, 0, 0x14000
	v_lshlrev_b32_e32 v6, 4, v6
	s_ashr_i32 s53, s48, 1
	v_add3_u32 v6, s6, v7, v6
	s_and_b32 s6, s53, 1
	s_and_b32 s52, s48, 1
	v_add_u32_e32 v3, s91, v3
	s_cmp_eq_u32 s6, 0
	ds_write_b16 v3, v2
	v_cvt_pk_bf16_f32 v2, v9, s0
	v_add_u32_e32 v3, s91, v4
	s_cselect_b64 s[8:9], -1, 0
	s_bitcmp1_b32 s48, 0
	ds_write_b16 v3, v2
	v_cvt_pk_bf16_f32 v4, v12, v13
	v_cvt_pk_bf16_f32 v3, v22, v23
	v_cvt_pk_bf16_f32 v2, v28, v29
	s_cselect_b64 s[10:11], -1, 0
	ds_write_b128 v6, v[2:5]
	v_cvt_pk_bf16_f32 v5, v8, v9
	v_cvt_pk_bf16_f32 v4, v10, v11
	v_cvt_pk_bf16_f32 v3, v18, v19
	v_cvt_pk_bf16_f32 v2, v26, v27
	s_and_b64 s[8:9], s[8:9], s[10:11]
	ds_write_b128 v6, v[2:5] offset:8192
	v_and_b32_e32 v94, 31, v1
	v_lshrrev_b32_e32 v95, 5, v93
	v_mov_b32_e32 v2, 0
	s_and_b64 vcc, exec, s[8:9]
	v_mov_b32_e32 v3, 0
	v_mov_b32_e32 v4, 0
	v_mov_b32_e32 v5, 0
	v_mov_b32_e32 v6, 0
	v_mov_b32_e32 v7, 0
	v_mov_b32_e32 v8, 0
	v_mov_b32_e32 v9, 0
	v_mov_b32_e32 v10, 0
	v_mov_b32_e32 v11, 0
	v_mov_b32_e32 v12, 0
	v_mov_b32_e32 v13, 0
	v_mov_b32_e32 v14, 0
	v_mov_b32_e32 v15, 0
	v_mov_b32_e32 v16, 0
	v_mov_b32_e32 v17, 0
	s_waitcnt lgkmcnt(0)
	s_barrier
	s_cbranch_vccz .LBB0_136
	s_cmp_gt_u32 s48, 3
	v_lshlrev_b32_e32 v25, 2, v95
	s_mov_b64 s[28:29], -1
	s_cbranch_scc1 .LBB0_137

.LBB0_206:
	s_add_i32 s6, s48, -4
	v_lshlrev_b32_e32 v2, 9, v94
	v_lshlrev_b32_e32 v3, 2, v94
	v_lshlrev_b32_e32 v4, 11, v95
	v_lshlrev_b32_e32 v8, 4, v95
	s_lshl_b32 s7, s6, 6
	v_lshl_add_u32 v2, v95, 4, v2
	v_add_u32_e32 v3, 0x24b00, v3
	v_lshl_add_u32 v4, v94, 2, v4
	v_add_u32_e32 v8, s7, v8
	v_add_u32_e32 v2, s7, v2
	s_lshl_b32 s7, s6, 13
	s_add_i32 s7, s7, 0x8000
	v_add_u32_e32 v8, 0x24c00, v8
	v_add_u32_e32 v4, s7, v4
	s_lshl_b32 s7, s6, 10
	s_add_i32 s7, s7, s51
	v_add_u32_e32 v5, 0x80, v4
	v_lshl_add_u32 v9, v93, 4, s7
	ds_read_b32 v182, v3
	ds_read_b32 v184, v3 offset:128
	ds_read_b128 v[150:153], v2
	ds_read_b128 v[154:157], v2 offset:32
	ds_read_b128 v[158:161], v2 offset:256
	ds_read_b128 v[162:165], v2 offset:288
	ds_read_b128 v[166:169], v2 offset:16384
	ds_read_b128 v[170:173], v2 offset:16416
	ds_read_b128 v[174:177], v2 offset:16640
	ds_read_b128 v[178:181], v2 offset:16672
	ds_read_b128 v[186:189], v8
	ds_read_b128 v[190:193], v8 offset:32
	s_waitcnt lgkmcnt(2)
	ds_read2st64_b32 v[194:195], v4 offset1:2
	ds_read2st64_b32 v[196:197], v4 offset0:4 offset1:6
	ds_read2st64_b32 v[198:199], v4 offset0:16 offset1:18
	ds_read2st64_b32 v[200:201], v4 offset0:20 offset1:22
	ds_read2st64_b32 v[202:203], v5 offset1:2
	ds_read2st64_b32 v[204:205], v5 offset0:4 offset1:6
	ds_read2st64_b32 v[206:207], v5 offset0:16 offset1:18
	ds_read2st64_b32 v[208:209], v5 offset0:20 offset1:22
	v_pk_mul_f32 v[150:151], v[150:151], v[182:183] op_sel_hi:[1,0]
	v_pk_mul_f32 v[152:153], v[152:153], v[182:183] op_sel_hi:[1,0]
	v_pk_mul_f32 v[154:155], v[154:155], v[182:183] op_sel_hi:[1,0]
	v_pk_mul_f32 v[156:157], v[156:157], v[182:183] op_sel_hi:[1,0]
	v_cvt_pk_bf16_f32 v10, v150, v151
	v_cvt_pk_bf16_f32 v11, v152, v153
	v_cvt_pk_bf16_f32 v12, v154, v155
	v_cvt_pk_bf16_f32 v13, v156, v157
	v_add_u32_e32 v6, 0x4000, v9
	buffer_store_dwordx4 v[10:13], v6, s[72:75], 0 offen sc1
	v_pk_mul_f32 v[158:159], v[158:159], v[182:183] op_sel_hi:[1,0]
	v_pk_mul_f32 v[160:161], v[160:161], v[182:183] op_sel_hi:[1,0]
	v_pk_mul_f32 v[162:163], v[162:163], v[182:183] op_sel_hi:[1,0]
	v_pk_mul_f32 v[164:165], v[164:165], v[182:183] op_sel_hi:[1,0]
	v_cvt_pk_bf16_f32 v14, v158, v159
	v_cvt_pk_bf16_f32 v15, v160, v161
	v_cvt_pk_bf16_f32 v16, v162, v163
	v_cvt_pk_bf16_f32 v17, v164, v165
	v_add_u32_e32 v7, 0x5000, v9
	buffer_store_dwordx4 v[14:17], v7, s[72:75], 0 offen sc1
	v_pk_mul_f32 v[166:167], v[166:167], v[184:185] op_sel_hi:[1,0]
	v_pk_mul_f32 v[168:169], v[168:169], v[184:185] op_sel_hi:[1,0]
	v_pk_mul_f32 v[170:171], v[170:171], v[184:185] op_sel_hi:[1,0]
	v_pk_mul_f32 v[172:173], v[172:173], v[184:185] op_sel_hi:[1,0]
	v_cvt_pk_bf16_f32 v18, v166, v167
	v_cvt_pk_bf16_f32 v19, v168, v169
	v_cvt_pk_bf16_f32 v20, v170, v171
	v_cvt_pk_bf16_f32 v21, v172, v173
	v_add_u32_e32 v6, 0x6000, v9
	buffer_store_dwordx4 v[18:21], v6, s[72:75], 0 offen sc1
	v_pk_mul_f32 v[174:175], v[174:175], v[184:185] op_sel_hi:[1,0]
	v_pk_mul_f32 v[176:177], v[176:177], v[184:185] op_sel_hi:[1,0]
	v_pk_mul_f32 v[178:179], v[178:179], v[184:185] op_sel_hi:[1,0]
	v_pk_mul_f32 v[180:181], v[180:181], v[184:185] op_sel_hi:[1,0]
	v_cvt_pk_bf16_f32 v26, v174, v175
	v_cvt_pk_bf16_f32 v27, v176, v177
	v_cvt_pk_bf16_f32 v28, v178, v179
	v_cvt_pk_bf16_f32 v29, v180, v181
	v_add_u32_e32 v7, 0x7000, v9
	buffer_store_dwordx4 v[26:29], v7, s[72:75], 0 offen sc1
	s_waitcnt lgkmcnt(4)
	ds_read2st64_b32 v[210:211], v4 offset0:1 offset1:3
	ds_read2st64_b32 v[212:213], v4 offset0:5 offset1:7
	ds_read2st64_b32 v[214:215], v4 offset0:17 offset1:19
	ds_read2st64_b32 v[216:217], v4 offset0:21 offset1:23
	ds_read2st64_b32 v[106:107], v5 offset0:1 offset1:3
	ds_read2st64_b32 v[108:109], v5 offset0:5 offset1:7
	ds_read2st64_b32 v[110:111], v5 offset0:17 offset1:19
	ds_read2st64_b32 v[112:113], v5 offset0:21 offset1:23
	v_pk_mul_f32 v[194:195], v[194:195], v[186:187]
	v_pk_mul_f32 v[196:197], v[196:197], v[188:189]
	v_pk_mul_f32 v[198:199], v[198:199], v[190:191]
	v_pk_mul_f32 v[200:201], v[200:201], v[192:193]
	v_cvt_pk_bf16_f32 v30, v194, v195
	v_cvt_pk_bf16_f32 v31, v196, v197
	v_cvt_pk_bf16_f32 v32, v198, v199
	v_cvt_pk_bf16_f32 v33, v200, v201
	v_add_u32_e32 v6, 0xa000, v9
	buffer_store_dwordx4 v[30:33], v6, s[72:75], 0 offen sc1
	s_waitcnt lgkmcnt(8)
	v_pk_mul_f32 v[202:203], v[202:203], v[186:187]
	v_pk_mul_f32 v[204:205], v[204:205], v[188:189]
	v_pk_mul_f32 v[206:207], v[206:207], v[190:191]
	v_pk_mul_f32 v[208:209], v[208:209], v[192:193]
	v_cvt_pk_bf16_f32 v114, v202, v203
	v_cvt_pk_bf16_f32 v115, v204, v205
	v_cvt_pk_bf16_f32 v116, v206, v207
	v_cvt_pk_bf16_f32 v117, v208, v209
	v_add_u32_e32 v7, 0xb000, v9
	buffer_store_dwordx4 v[114:117], v7, s[72:75], 0 offen sc1
	s_waitcnt lgkmcnt(4)
	v_pk_mul_f32 v[210:211], v[210:211], v[186:187]
	v_pk_mul_f32 v[212:213], v[212:213], v[188:189]
	v_pk_mul_f32 v[214:215], v[214:215], v[190:191]
	v_pk_mul_f32 v[216:217], v[216:217], v[192:193]
	v_cvt_pk_bf16_f32 v118, v210, v211
	v_cvt_pk_bf16_f32 v119, v212, v213
	v_cvt_pk_bf16_f32 v120, v214, v215
	v_cvt_pk_bf16_f32 v121, v216, v217
	v_add_u32_e32 v6, 0xc000, v9
	buffer_store_dwordx4 v[118:121], v6, s[72:75], 0 offen sc1
	s_waitcnt lgkmcnt(0)
	v_pk_mul_f32 v[106:107], v[106:107], v[186:187]
	v_pk_mul_f32 v[108:109], v[108:109], v[188:189]
	v_pk_mul_f32 v[110:111], v[110:111], v[190:191]
	v_pk_mul_f32 v[112:113], v[112:113], v[192:193]
	v_cvt_pk_bf16_f32 v122, v106, v107
	v_cvt_pk_bf16_f32 v123, v108, v109
	v_cvt_pk_bf16_f32 v124, v110, v111
	v_cvt_pk_bf16_f32 v125, v112, v113
	v_add_u32_e32 v7, 0xd000, v9
	buffer_store_dwordx4 v[122:125], v7, s[72:75], 0 offen sc1
